# stack + phase_prep p->bf16 conversion loop software-pipelined (next item's loads in flight during convert/store)
# baseline (speedup 1.0000x reference)
; DI void phase_prep(const Params& P, int l, char* shm) {
;     ...
;   {
;     const float* src = P.p + (size_t)l * T_TOK * 256;
;     u16* dst = (u16*)(P.ws + OFF_PB);
;     for (int i = gtid; i < T_TOK * 256 / 8; i += gn) {
;       float4 a = *(const float4*)(src + (size_t)i * 8), b = *(const float4*)(src + (size_t)i * 8 + 4);
;       i32x4 o;
;       o[0] = (int)pack2(a.x, a.y); o[1] = (int)pack2(a.z, a.w); o[2] = (int)pack2(b.x, b.y); o[3] = (int)pack2(b.z, b.w);
;       *(i32x4*)(dst + (size_t)i * 8) = o;
;     }
;   }
.Lpc_loopA:
	v_add_u32_e32 v0, s4, v0
	v_cmp_lt_i32_e32 vcc, s29, v0
	v_lshl_add_u64 v[4:5], v[4:5], 0, s[8:9]
	s_or_b64 s[10:11], vcc, s[10:11]
	s_andn2_b64 s[14:15], exec, s[10:11]
	s_cmp_eq_u64 s[14:15], 0
	s_cbranch_scc1 .Lpc_lastA
	s_mov_b64 s[12:13], exec
	s_mov_b64 exec, s[14:15]
	global_load_dwordx4 v[20:23], v[4:5], off offset:-16
	global_load_dwordx4 v[24:27], v[4:5], off
	s_mov_b64 exec, s[12:13]
	s_waitcnt vmcnt(2)
	v_cvt_pk_bf16_f32 v6, v6, v7
	v_cvt_pk_bf16_f32 v7, v8, v9
	v_cvt_pk_bf16_f32 v8, v10, v11
	v_cvt_pk_bf16_f32 v9, v12, v13
	global_store_dwordx4 v[2:3], v[6:9], off
	v_lshl_add_u64 v[2:3], v[2:3], 0, s[0:1]
	s_mov_b64 exec, s[14:15]
.Lpc_loopB:
	v_add_u32_e32 v0, s4, v0
	v_cmp_lt_i32_e32 vcc, s29, v0
	v_lshl_add_u64 v[4:5], v[4:5], 0, s[8:9]
	s_or_b64 s[10:11], vcc, s[10:11]
	s_andn2_b64 s[14:15], exec, s[10:11]
	s_cmp_eq_u64 s[14:15], 0
	s_cbranch_scc1 .Lpc_lastB
	s_mov_b64 s[12:13], exec
	s_mov_b64 exec, s[14:15]
	global_load_dwordx4 v[6:9], v[4:5], off offset:-16
	global_load_dwordx4 v[10:13], v[4:5], off
	s_mov_b64 exec, s[12:13]
	s_waitcnt vmcnt(2)
	v_cvt_pk_bf16_f32 v20, v20, v21
	v_cvt_pk_bf16_f32 v21, v22, v23
	v_cvt_pk_bf16_f32 v22, v24, v25
	v_cvt_pk_bf16_f32 v23, v26, v27
	global_store_dwordx4 v[2:3], v[20:23], off
	v_lshl_add_u64 v[2:3], v[2:3], 0, s[0:1]
	s_mov_b64 exec, s[14:15]
	s_branch .Lpc_loopA
.Lpc_lastA:
	s_waitcnt vmcnt(0)
	v_cvt_pk_bf16_f32 v6, v6, v7
	v_cvt_pk_bf16_f32 v7, v8, v9
	v_cvt_pk_bf16_f32 v8, v10, v11
	v_cvt_pk_bf16_f32 v9, v12, v13
	global_store_dwordx4 v[2:3], v[6:9], off
	s_branch .Lpc_done
.Lpc_lastB:
	s_waitcnt vmcnt(0)
	v_cvt_pk_bf16_f32 v20, v20, v21
	v_cvt_pk_bf16_f32 v21, v22, v23
	v_cvt_pk_bf16_f32 v22, v24, v25
	v_cvt_pk_bf16_f32 v23, v26, v27
	global_store_dwordx4 v[2:3], v[20:23], off
.Lpc_done:
	s_andn2_b64 exec, exec, s[10:11]
